# grid barrier inside the token-half loop: generation by one comparison instead of the reciprocal division
# baseline (speedup 1.0000x reference)
;     __device__ __forceinline__ const char* b(const Unit& u) const { return (const char*)Bt + (size_t)u.pn * 2 * hB() + (size_t)(u.pm >> gshift) * goff; }
;     __device__ __forceinline__ const char* b(const Unit& u) const { return (const char*)Bt + (size_t)((u.pn >> 4) * 4096 + (u.pn & 15) * 16) * 1024 * 2 + (size_t)(u.pm >> 1) * 512; }
;     __device__ __forceinline__ const char* b(const Unit& u) const { return (const char*)Bt + ((size_t)(((u.pm >> 4) * 1024 + u.pn * 256) * 16 + (u.pm & 15)) * 512) * 2; }
; __device__ __forceinline__ unsigned xb_ld(unsigned* p)              { return __hip_atomic_load(p, __ATOMIC_RELAXED, __HIP_MEMORY_SCOPE_AGENT); }
; __device__ __forceinline__ unsigned xb_add(unsigned* p, unsigned v) { return __hip_atomic_fetch_add(p, v, __ATOMIC_RELAXED, __HIP_MEMORY_SCOPE_AGENT); }
; #define XB_SPIN(cond, bar) do { unsigned _sp = 0; while (cond) { __builtin_amdgcn_s_sleep(1); \
;     if ((++_sp & 255u) == 0u) { if (xb_ld(&(bar)[XB_TMO])) break; if (_sp > XB_SPIN_CAP) { atomicAdd(&(bar)[XB_TMO], 1u); break; } } } } while (0)
; __device__ __forceinline__ void xcd_barrier(const XcdBarrier& b, const int wave) {
;     ...
;         const unsigned old = xb_add(&bar[XB_XSUB(b.x)], 1u);
;         const unsigned gen = old / nloc;
;         if (old + 1u == (gen + 1u) * nloc) {
;             __builtin_amdgcn_fence(__ATOMIC_RELEASE, "agent");
;             asm volatile("s_waitcnt vmcnt(0)" ::: "memory");
;             const unsigned og = xb_add(&bar[XB_TOP], 1u);
;             const unsigned tg = og / nx;
;             if (og + 1u == (tg + 1u) * nx) xb_add(&bar[XB_TOPGEN], 1u);
;             else XB_SPIN(xb_ld(&bar[XB_TOPGEN]) == tg, bar);
;             __builtin_amdgcn_fence(__ATOMIC_ACQUIRE, "agent");
;             xb_add(&bar[XB_XGEN(b.x)], 1u);
;             asm volatile("s_waitcnt vmcnt(0)" ::: "memory");
;         } else {
;             XB_SPIN(xb_ld(&bar[XB_XGEN(b.x)]) == gen, bar);
.LBB0_742:
	s_or_b64 exec, exec, s[22:23]
	s_waitcnt vmcnt(0)
	v_readfirstlane_b32 s0, v3
	v_add_u32_e32 v5, s0, v1
	v_add_u32_e32 v3, 1, v5
	v_mul_u32_u24_e32 v4, 6, v2
	v_cmp_ge_u32_e32 vcc, v5, v4
	s_nop 1
	v_cndmask_b32_e64 v1, 5, 6, vcc
	v_cndmask_b32_e64 v2, 0, v2, vcc
	v_add_u32_e32 v2, v4, v2
	v_cmp_ne_u32_e32 vcc, v3, v2
	s_and_saveexec_b64 s[0:1], vcc
	s_xor_b64 s[22:23], exec, s[0:1]
	s_cbranch_execz .LBB0_756
	v_readlane_b32 s0, v254, 32
	v_readlane_b32 s1, v254, 33
	s_waitcnt lgkmcnt(0)
	s_nop 3
	global_load_dword v0, v193, s[0:1] sc1
	s_waitcnt vmcnt(0)
	v_cmp_eq_u32_e32 vcc, v0, v1
	s_and_saveexec_b64 s[24:25], vcc
	s_cbranch_execz .LBB0_755
	s_mov_b32 s0, 1
	s_mov_b64 s[26:27], 0
	s_branch .LBB0_746

; __device__ __forceinline__ unsigned xb_ld(unsigned* p)              { return __hip_atomic_load(p, __ATOMIC_RELAXED, __HIP_MEMORY_SCOPE_AGENT); }
; __device__ __forceinline__ unsigned xb_add(unsigned* p, unsigned v) { return __hip_atomic_fetch_add(p, v, __ATOMIC_RELAXED, __HIP_MEMORY_SCOPE_AGENT); }
; #define XB_SPIN(cond, bar) do { unsigned _sp = 0; while (cond) { __builtin_amdgcn_s_sleep(1); \
;     if ((++_sp & 255u) == 0u) { if (xb_ld(&(bar)[XB_TMO])) break; if (_sp > XB_SPIN_CAP) { atomicAdd(&(bar)[XB_TMO], 1u); break; } } } } while (0)
; __device__ __forceinline__ void xcd_barrier(const XcdBarrier& b, const int wave) {
;     ...
;             const unsigned og = xb_add(&bar[XB_TOP], 1u);
;             const unsigned tg = og / nx;
;             if (og + 1u == (tg + 1u) * nx) xb_add(&bar[XB_TOPGEN], 1u);
;             else XB_SPIN(xb_ld(&bar[XB_TOPGEN]) == tg, bar);
.LBB0_759:
	s_or_b64 exec, exec, s[24:25]
	s_waitcnt vmcnt(0)
	v_readfirstlane_b32 s0, v2
	v_add_u32_e32 v1, s0, v1
	v_readlane_b32 s0, v254, 14
	v_readlane_b32 s1, v254, 15
	s_mov_b64 s[24:25], -1
	v_mul_u32_u24_e32 v4, 6, v0
	v_cmp_ge_u32_e32 vcc, v1, v4
	s_nop 1
	v_cndmask_b32_e64 v2, 5, 6, vcc
	v_cndmask_b32_e64 v0, 0, v0, vcc
	v_add_u32_e32 v0, v4, v0
	v_add_u32_e32 v1, 1, v1
	v_cmp_ne_u32_e32 vcc, v1, v0
	v_mov_b64_e32 v[0:1], s[0:1]
	s_and_saveexec_b64 s[22:23], vcc
	s_cbranch_execz .LBB0_771
	v_readlane_b32 s0, v254, 14
	v_readlane_b32 s1, v254, 15
	s_mov_b64 s[26:27], 0
	s_nop 3
	global_load_dword v0, v193, s[0:1] sc1
	s_waitcnt vmcnt(0)
	v_cmp_eq_u32_e32 vcc, v0, v2
	s_and_saveexec_b64 s[24:25], vcc
	s_cbranch_execz .LBB0_770
	s_mov_b32 s0, 1
	s_branch .LBB0_763
